# v59: first workgroup to arrive in each XCD issues an early L2 writeback (overlaps the flush of finished tiles with the stragglers' work)
# speedup vs baseline: 1.0045x; 1.0045x over previous
; __device__ __forceinline__ unsigned xb_add(unsigned* p, unsigned v) { return __hip_atomic_fetch_add(p, v, __ATOMIC_RELAXED, __HIP_MEMORY_SCOPE_AGENT); }
; __device__ __forceinline__ void xcd_barrier(const XcdBarrier& b) {
;     ...
;         const unsigned old = xb_add(&bar[XB_XSUB(b.x)], 1u);
;         const unsigned gen = old / nloc;
;         if (old + 1u == (gen + 1u) * nloc) {
;             __builtin_amdgcn_fence(__ATOMIC_RELEASE, "agent");
;             asm volatile("s_waitcnt vmcnt(0)" ::: "memory");
;             const unsigned og = xb_add(&bar[XB_TOP], 1u);
;             const unsigned tg = og / nx;
;             if (og + 1u == (tg + 1u) * nx) xb_add(&bar[XB_TOPGEN], 1u);
.LBB0_82:
	v_mov_b32_e32 v4, 0x20000
	ds_read2_b32 v[2:3], v4 offset1:1
	v_readlane_b32 s3, v244, 30
	s_nop 0
	s_lshl_b32 s3, s3, 8
	s_getpc_b64 s[4:5]
	s_add_u32 s4, s4, g_xbar@rel32@lo+4
	s_addc_u32 s5, s5, g_xbar@rel32@hi+12
	s_add_u32 s4, s4, s3
	s_addc_u32 s5, s5, 0
	v_mov_b32_e32 v5, 0x1000
	v_mov_b32_e32 v6, 1
	global_atomic_add v5, v5, v6, s[4:5] offset:1024 sc0
	s_movk_i32 s3, 1
	s_waitcnt lgkmcnt(0)
	v_mul_lo_u32 v4, v2, s3
	v_mul_lo_u32 v3, v3, s3
	s_waitcnt vmcnt(0)
	v_add_u32_e32 v2, v2, v5
	v_cmp_eq_u32_e32 vcc, v2, v4
	s_cbranch_vccz .Lfb0_noearly
	buffer_wbl2 sc1
.Lfb0_noearly:
	v_add_u32_e32 v5, 1, v5
	v_cmp_ne_u32_e32 vcc, v5, v4
	s_getpc_b64 s[4:5]
	s_add_u32 s4, s4, g_xbar@rel32@lo+13316
	s_addc_u32 s5, s5, g_xbar@rel32@hi+13324
	v_mov_b32_e32 v4, 0
	s_cbranch_vccnz .Lfb0_spin0
	buffer_wbl2 sc1
	s_waitcnt vmcnt(0) lgkmcnt(0)
	global_atomic_add v4, v6, s[4:5]

; __device__ __forceinline__ unsigned xb_add(unsigned* p, unsigned v) { return __hip_atomic_fetch_add(p, v, __ATOMIC_RELAXED, __HIP_MEMORY_SCOPE_AGENT); }
; __device__ __forceinline__ void xcd_barrier(const XcdBarrier& b) {
;     ...
;         const unsigned old = xb_add(&bar[XB_XSUB(b.x)], 1u);
;         const unsigned gen = old / nloc;
;         if (old + 1u == (gen + 1u) * nloc) {
;             __builtin_amdgcn_fence(__ATOMIC_RELEASE, "agent");
;             asm volatile("s_waitcnt vmcnt(0)" ::: "memory");
;             const unsigned og = xb_add(&bar[XB_TOP], 1u);
;             const unsigned tg = og / nx;
;             if (og + 1u == (tg + 1u) * nx) xb_add(&bar[XB_TOPGEN], 1u);
.LBB0_464:
	v_mov_b32_e32 v4, 0x20000
	ds_read2_b32 v[2:3], v4 offset1:1
	v_readlane_b32 s3, v244, 30
	s_nop 0
	s_lshl_b32 s3, s3, 8
	s_getpc_b64 s[4:5]
	s_add_u32 s4, s4, g_xbar@rel32@lo+4
	s_addc_u32 s5, s5, g_xbar@rel32@hi+12
	s_add_u32 s4, s4, s3
	s_addc_u32 s5, s5, 0
	v_mov_b32_e32 v5, 0x1000
	v_mov_b32_e32 v6, 1
	global_atomic_add v5, v5, v6, s[4:5] offset:1024 sc0
	s_movk_i32 s3, 2
	s_waitcnt lgkmcnt(0)
	v_mul_lo_u32 v4, v2, s3
	v_mul_lo_u32 v3, v3, s3
	s_waitcnt vmcnt(0)
	v_add_u32_e32 v2, v2, v5
	v_cmp_eq_u32_e32 vcc, v2, v4
	s_cbranch_vccz .Lfb1_noearly
	buffer_wbl2 sc1

; __device__ __forceinline__ unsigned xb_add(unsigned* p, unsigned v) { return __hip_atomic_fetch_add(p, v, __ATOMIC_RELAXED, __HIP_MEMORY_SCOPE_AGENT); }
; __device__ __forceinline__ void xcd_barrier(const XcdBarrier& b) {
;     ...
;         const unsigned old = xb_add(&bar[XB_XSUB(b.x)], 1u);
;         const unsigned gen = old / nloc;
;         if (old + 1u == (gen + 1u) * nloc) {
;             __builtin_amdgcn_fence(__ATOMIC_RELEASE, "agent");
;             asm volatile("s_waitcnt vmcnt(0)" ::: "memory");
;             const unsigned og = xb_add(&bar[XB_TOP], 1u);
;             const unsigned tg = og / nx;
;             if (og + 1u == (tg + 1u) * nx) xb_add(&bar[XB_TOPGEN], 1u);
.LBB0_594:
	v_mov_b32_e32 v4, 0x20000
	ds_read2_b32 v[2:3], v4 offset1:1
	v_readlane_b32 s6, v244, 30
	s_nop 0
	s_lshl_b32 s6, s6, 8
	s_getpc_b64 s[4:5]
	s_add_u32 s4, s4, g_xbar@rel32@lo+4
	s_addc_u32 s5, s5, g_xbar@rel32@hi+12
	s_add_u32 s4, s4, s6
	s_addc_u32 s5, s5, 0
	v_mov_b32_e32 v5, 0x1000
	v_mov_b32_e32 v6, 1
	global_atomic_add v5, v5, v6, s[4:5] offset:1024 sc0
	s_movk_i32 s6, 3
	s_waitcnt lgkmcnt(0)
	v_mul_lo_u32 v4, v2, s6
	v_mul_lo_u32 v3, v3, s6
	s_waitcnt vmcnt(0)
	v_add_u32_e32 v2, v2, v5
	v_cmp_eq_u32_e32 vcc, v2, v4
	s_cbranch_vccz .Lfb2_noearly
	buffer_wbl2 sc1

; __device__ __forceinline__ unsigned xb_add(unsigned* p, unsigned v) { return __hip_atomic_fetch_add(p, v, __ATOMIC_RELAXED, __HIP_MEMORY_SCOPE_AGENT); }
; __device__ __forceinline__ void xcd_barrier(const XcdBarrier& b) {
;     ...
;         const unsigned old = xb_add(&bar[XB_XSUB(b.x)], 1u);
;         const unsigned gen = old / nloc;
;         if (old + 1u == (gen + 1u) * nloc) {
;             __builtin_amdgcn_fence(__ATOMIC_RELEASE, "agent");
;             asm volatile("s_waitcnt vmcnt(0)" ::: "memory");
;             const unsigned og = xb_add(&bar[XB_TOP], 1u);
;             const unsigned tg = og / nx;
;             if (og + 1u == (tg + 1u) * nx) xb_add(&bar[XB_TOPGEN], 1u);
.LBB0_684:
	v_mov_b32_e32 v4, 0x20000
	ds_read2_b32 v[2:3], v4 offset1:1
	v_readlane_b32 s6, v244, 30
	s_nop 0
	s_lshl_b32 s6, s6, 8
	s_getpc_b64 s[4:5]
	s_add_u32 s4, s4, g_xbar@rel32@lo+4
	s_addc_u32 s5, s5, g_xbar@rel32@hi+12
	s_add_u32 s4, s4, s6
	s_addc_u32 s5, s5, 0
	v_mov_b32_e32 v5, 0x1000
	v_mov_b32_e32 v6, 1
	global_atomic_add v5, v5, v6, s[4:5] offset:1024 sc0
	s_movk_i32 s6, 4
	s_waitcnt lgkmcnt(0)
	v_mul_lo_u32 v4, v2, s6
	v_mul_lo_u32 v3, v3, s6
	s_waitcnt vmcnt(0)
	v_add_u32_e32 v2, v2, v5
	v_cmp_eq_u32_e32 vcc, v2, v4
	s_cbranch_vccz .Lfb3_noearly
	buffer_wbl2 sc1

; __device__ __forceinline__ unsigned xb_add(unsigned* p, unsigned v) { return __hip_atomic_fetch_add(p, v, __ATOMIC_RELAXED, __HIP_MEMORY_SCOPE_AGENT); }
; __device__ __forceinline__ void xcd_barrier(const XcdBarrier& b) {
;     ...
;         const unsigned old = xb_add(&bar[XB_XSUB(b.x)], 1u);
;         const unsigned gen = old / nloc;
;         if (old + 1u == (gen + 1u) * nloc) {
;             __builtin_amdgcn_fence(__ATOMIC_RELEASE, "agent");
;             asm volatile("s_waitcnt vmcnt(0)" ::: "memory");
;             const unsigned og = xb_add(&bar[XB_TOP], 1u);
;             const unsigned tg = og / nx;
;             if (og + 1u == (tg + 1u) * nx) xb_add(&bar[XB_TOPGEN], 1u);
.LBB0_763:
	v_mov_b32_e32 v4, 0x20000
	ds_read2_b32 v[2:3], v4 offset1:1
	v_readlane_b32 s6, v244, 30
	s_nop 0
	s_lshl_b32 s6, s6, 8
	s_getpc_b64 s[4:5]
	s_add_u32 s4, s4, g_xbar@rel32@lo+4
	s_addc_u32 s5, s5, g_xbar@rel32@hi+12
	s_add_u32 s4, s4, s6
	s_addc_u32 s5, s5, 0
	v_mov_b32_e32 v5, 0x1000
	v_mov_b32_e32 v6, 1
	global_atomic_add v5, v5, v6, s[4:5] offset:1024 sc0
	s_movk_i32 s6, 5
	s_waitcnt lgkmcnt(0)
	v_mul_lo_u32 v4, v2, s6
	v_mul_lo_u32 v3, v3, s6
	s_waitcnt vmcnt(0)
	v_add_u32_e32 v2, v2, v5
	v_cmp_eq_u32_e32 vcc, v2, v4
	s_cbranch_vccz .Lfb4_noearly
	buffer_wbl2 sc1

; __device__ __forceinline__ unsigned xb_add(unsigned* p, unsigned v) { return __hip_atomic_fetch_add(p, v, __ATOMIC_RELAXED, __HIP_MEMORY_SCOPE_AGENT); }
; __device__ __forceinline__ void xcd_barrier(const XcdBarrier& b) {
;     ...
;         const unsigned old = xb_add(&bar[XB_XSUB(b.x)], 1u);
;         const unsigned gen = old / nloc;
;         if (old + 1u == (gen + 1u) * nloc) {
;             __builtin_amdgcn_fence(__ATOMIC_RELEASE, "agent");
;             asm volatile("s_waitcnt vmcnt(0)" ::: "memory");
;             const unsigned og = xb_add(&bar[XB_TOP], 1u);
;             const unsigned tg = og / nx;
;             if (og + 1u == (tg + 1u) * nx) xb_add(&bar[XB_TOPGEN], 1u);
.LBB0_853:
	v_mov_b32_e32 v4, 0x20000
	ds_read2_b32 v[2:3], v4 offset1:1
	v_readlane_b32 s6, v244, 30
	s_nop 0
	s_lshl_b32 s6, s6, 8
	s_getpc_b64 s[4:5]
	s_add_u32 s4, s4, g_xbar@rel32@lo+4
	s_addc_u32 s5, s5, g_xbar@rel32@hi+12
	s_add_u32 s4, s4, s6
	s_addc_u32 s5, s5, 0
	v_mov_b32_e32 v5, 0x1000
	v_mov_b32_e32 v6, 1
	global_atomic_add v5, v5, v6, s[4:5] offset:1024 sc0
	s_movk_i32 s6, 6
	s_waitcnt lgkmcnt(0)
	v_mul_lo_u32 v4, v2, s6
	v_mul_lo_u32 v3, v3, s6
	s_waitcnt vmcnt(0)
	v_add_u32_e32 v2, v2, v5
	v_cmp_eq_u32_e32 vcc, v2, v4
	s_cbranch_vccz .Lfb5_noearly
	buffer_wbl2 sc1

; __device__ __forceinline__ unsigned xb_add(unsigned* p, unsigned v) { return __hip_atomic_fetch_add(p, v, __ATOMIC_RELAXED, __HIP_MEMORY_SCOPE_AGENT); }
; __device__ __forceinline__ void xcd_barrier(const XcdBarrier& b) {
;     ...
;         const unsigned old = xb_add(&bar[XB_XSUB(b.x)], 1u);
;         const unsigned gen = old / nloc;
;         if (old + 1u == (gen + 1u) * nloc) {
;             __builtin_amdgcn_fence(__ATOMIC_RELEASE, "agent");
;             asm volatile("s_waitcnt vmcnt(0)" ::: "memory");
;             const unsigned og = xb_add(&bar[XB_TOP], 1u);
;             const unsigned tg = og / nx;
;             if (og + 1u == (tg + 1u) * nx) xb_add(&bar[XB_TOPGEN], 1u);
.LBB0_915:
	v_mov_b32_e32 v4, 0x20000
	ds_read2_b32 v[2:3], v4 offset1:1
	v_readlane_b32 s3, v244, 30
	s_nop 0
	s_lshl_b32 s3, s3, 8
	s_getpc_b64 s[8:9]
	s_add_u32 s8, s8, g_xbar@rel32@lo+4
	s_addc_u32 s9, s9, g_xbar@rel32@hi+12
	s_add_u32 s8, s8, s3
	s_addc_u32 s9, s9, 0
	v_mov_b32_e32 v5, 0x1000
	v_mov_b32_e32 v6, 1
	global_atomic_add v5, v5, v6, s[8:9] offset:1024 sc0
	s_movk_i32 s3, 7
	s_waitcnt lgkmcnt(0)
	v_mul_lo_u32 v4, v2, s3
	v_mul_lo_u32 v3, v3, s3
	s_waitcnt vmcnt(0)
	v_add_u32_e32 v2, v2, v5
	v_cmp_eq_u32_e32 vcc, v2, v4
	s_cbranch_vccz .Lfb6_noearly
	buffer_wbl2 sc1
.Lfb6_noearly:
	v_add_u32_e32 v5, 1, v5
	v_cmp_ne_u32_e32 vcc, v5, v4
	s_getpc_b64 s[8:9]
	s_add_u32 s8, s8, g_xbar@rel32@lo+13316
	s_addc_u32 s9, s9, g_xbar@rel32@hi+13324
	v_mov_b32_e32 v4, 0
	s_cbranch_vccnz .Lfb6_spin0
	buffer_wbl2 sc1
	s_waitcnt vmcnt(0) lgkmcnt(0)
	global_atomic_add v4, v6, s[8:9]

; __device__ __forceinline__ unsigned xb_add(unsigned* p, unsigned v) { return __hip_atomic_fetch_add(p, v, __ATOMIC_RELAXED, __HIP_MEMORY_SCOPE_AGENT); }
; __device__ __forceinline__ void xcd_barrier(const XcdBarrier& b) {
;     ...
;         const unsigned old = xb_add(&bar[XB_XSUB(b.x)], 1u);
;         const unsigned gen = old / nloc;
;         if (old + 1u == (gen + 1u) * nloc) {
;             __builtin_amdgcn_fence(__ATOMIC_RELEASE, "agent");
;             asm volatile("s_waitcnt vmcnt(0)" ::: "memory");
;             const unsigned og = xb_add(&bar[XB_TOP], 1u);
;             const unsigned tg = og / nx;
;             if (og + 1u == (tg + 1u) * nx) xb_add(&bar[XB_TOPGEN], 1u);
.LBB0_1119:
	v_mov_b32_e32 v4, 0x20000
	ds_read2_b32 v[2:3], v4 offset1:1
	v_readlane_b32 s3, v244, 30
	s_nop 0
	s_lshl_b32 s3, s3, 8
	s_getpc_b64 s[8:9]
	s_add_u32 s8, s8, g_xbar@rel32@lo+4
	s_addc_u32 s9, s9, g_xbar@rel32@hi+12
	s_add_u32 s8, s8, s3
	s_addc_u32 s9, s9, 0
	v_mov_b32_e32 v5, 0x1000
	v_mov_b32_e32 v6, 1
	global_atomic_add v5, v5, v6, s[8:9] offset:1024 sc0
	s_movk_i32 s3, 8
	s_waitcnt lgkmcnt(0)
	v_mul_lo_u32 v4, v2, s3
	v_mul_lo_u32 v3, v3, s3
	s_waitcnt vmcnt(0)
	v_add_u32_e32 v2, v2, v5
	v_cmp_eq_u32_e32 vcc, v2, v4
	s_cbranch_vccz .Lfb7_noearly
	buffer_wbl2 sc1

; __device__ __forceinline__ unsigned xb_add(unsigned* p, unsigned v) { return __hip_atomic_fetch_add(p, v, __ATOMIC_RELAXED, __HIP_MEMORY_SCOPE_AGENT); }
; __device__ __forceinline__ void xcd_barrier(const XcdBarrier& b) {
;     ...
;         const unsigned old = xb_add(&bar[XB_XSUB(b.x)], 1u);
;         const unsigned gen = old / nloc;
;         if (old + 1u == (gen + 1u) * nloc) {
;             __builtin_amdgcn_fence(__ATOMIC_RELEASE, "agent");
;             asm volatile("s_waitcnt vmcnt(0)" ::: "memory");
;             const unsigned og = xb_add(&bar[XB_TOP], 1u);
;             const unsigned tg = og / nx;
;             if (og + 1u == (tg + 1u) * nx) xb_add(&bar[XB_TOPGEN], 1u);
.LBB0_1180:
	v_mov_b32_e32 v1, 0x20000
	ds_read2_b32 v[2:3], v1 offset1:1
	v_readlane_b32 s8, v244, 30
	s_nop 0
	s_lshl_b32 s8, s8, 8
	s_getpc_b64 s[6:7]
	s_add_u32 s6, s6, g_xbar@rel32@lo+4
	s_addc_u32 s7, s7, g_xbar@rel32@hi+12
	s_add_u32 s6, s6, s8
	s_addc_u32 s7, s7, 0
	v_mov_b32_e32 v4, 0x1000
	v_mov_b32_e32 v5, 1
	global_atomic_add v4, v4, v5, s[6:7] offset:1024 sc0
	s_movk_i32 s8, 9
	s_waitcnt lgkmcnt(0)
	v_mul_lo_u32 v1, v2, s8
	v_mul_lo_u32 v3, v3, s8
	s_waitcnt vmcnt(0)
	v_add_u32_e32 v2, v2, v4
	v_cmp_eq_u32_e32 vcc, v2, v1
	s_cbranch_vccz .Lfb8_noearly
	buffer_wbl2 sc1
.Lfb8_noearly:
	v_add_u32_e32 v4, 1, v4
	v_cmp_ne_u32_e32 vcc, v4, v1
	s_getpc_b64 s[6:7]
	s_add_u32 s6, s6, g_xbar@rel32@lo+13316
	s_addc_u32 s7, s7, g_xbar@rel32@hi+13324
	v_mov_b32_e32 v1, 0
	s_cbranch_vccnz .Lfb8_spin0
	buffer_wbl2 sc1
	s_waitcnt vmcnt(0) lgkmcnt(0)
	global_atomic_add v1, v5, s[6:7]

; __device__ __forceinline__ unsigned xb_add(unsigned* p, unsigned v) { return __hip_atomic_fetch_add(p, v, __ATOMIC_RELAXED, __HIP_MEMORY_SCOPE_AGENT); }
; __device__ __forceinline__ void xcd_barrier(const XcdBarrier& b) {
;     ...
;         const unsigned old = xb_add(&bar[XB_XSUB(b.x)], 1u);
;         const unsigned gen = old / nloc;
;         if (old + 1u == (gen + 1u) * nloc) {
;             __builtin_amdgcn_fence(__ATOMIC_RELEASE, "agent");
;             asm volatile("s_waitcnt vmcnt(0)" ::: "memory");
;             const unsigned og = xb_add(&bar[XB_TOP], 1u);
;             const unsigned tg = og / nx;
;             if (og + 1u == (tg + 1u) * nx) xb_add(&bar[XB_TOPGEN], 1u);
.LBB0_1274:
	v_mov_b32_e32 v2, 0x20000
	ds_read2_b32 v[0:1], v2 offset1:1
	v_readlane_b32 s8, v244, 30
	s_nop 0
	s_lshl_b32 s8, s8, 8
	s_getpc_b64 s[6:7]
	s_add_u32 s6, s6, g_xbar@rel32@lo+4
	s_addc_u32 s7, s7, g_xbar@rel32@hi+12
	s_add_u32 s6, s6, s8
	s_addc_u32 s7, s7, 0
	v_mov_b32_e32 v3, 0x1000
	v_mov_b32_e32 v4, 1
	global_atomic_add v3, v3, v4, s[6:7] offset:1024 sc0
	s_movk_i32 s8, 10
	s_waitcnt lgkmcnt(0)
	v_mul_lo_u32 v2, v0, s8
	v_mul_lo_u32 v1, v1, s8
	s_waitcnt vmcnt(0)
	v_add_u32_e32 v0, v0, v3
	v_cmp_eq_u32_e32 vcc, v0, v2
	s_cbranch_vccz .Lfb9_noearly
	buffer_wbl2 sc1
.Lfb9_noearly:
	v_add_u32_e32 v3, 1, v3
	v_cmp_ne_u32_e32 vcc, v3, v2
	s_getpc_b64 s[6:7]
	s_add_u32 s6, s6, g_xbar@rel32@lo+13316
	s_addc_u32 s7, s7, g_xbar@rel32@hi+13324
	v_mov_b32_e32 v2, 0
	s_cbranch_vccnz .Lfb9_spin0
	buffer_wbl2 sc1
	s_waitcnt vmcnt(0) lgkmcnt(0)
	global_atomic_add v2, v4, s[6:7]
